# attn: plain add row sums, permlane32_swap row max, hoisted K-frag reads d0=0,1
# speedup vs baseline: 1.0083x; 1.0083x over previous
; __device__ __forceinline__ unsigned cvtpk(float lo, float hi) { f32x2_t v = {lo, hi}; bf16x2_t b = __builtin_convertvector(v, bf16x2_t); return __builtin_bit_cast(unsigned, b); }
; __device__ __forceinline__ int crow(int r, int hi) { return (r & 3) + 8 * (r >> 2) + 4 * hi; }
; __device__ __forceinline__ void attn_unit(const Ctx& c, int bh, int qb, const bf16_t* Q, const bf16_t* Kb, const bf16_t* Vb, bf16_t* O) {
;     ...
;     lsum += __int_as_float(__builtin_amdgcn_ds_bpermute((lane ^ 32) * 4, __float_as_int(lsum)));
;     if (hi == 0) wsf[r32] = 1.0f / lsum;
;     asm volatile("" ::: "memory");
;     bf16_t* op = O + (rowbase + q0 + wid * 32) * 1024 + h * 64 + r32;
; #pragma unroll
;     for (int r = 0; r < 16; ++r) { const int qq = crow(r, hi); const float rl = wsf[qq];
;         op[(size_t)qq * 1024] = (bf16_t)(cvtpk(o[0][r] * rl, 0.f) & 0xffffu); op[(size_t)qq * 1024 + 32] = (bf16_t)(cvtpk(o[1][r] * rl, 0.f) & 0xffffu); }
;     asm volatile("" ::: "memory");
.LBB0_276:
	s_or_b64 exec, exec, s[6:7]
	v_or_b32_e32 v160, 0x800, v158
	v_mov_b32_e32 v161, v211
	v_or_b32_e32 v162, 0x1000, v158
	v_mov_b32_e32 v163, v211
	v_or_b32_e32 v164, 0x1800, v158
	v_mov_b32_e32 v165, v211
	v_or_b32_e32 v166, 0x4000, v158
	v_mov_b32_e32 v167, v211
	v_or_b32_e32 v168, 0x4800, v158
	v_mov_b32_e32 v169, v211
	v_or_b32_e32 v170, 0x5000, v158
	v_mov_b32_e32 v171, v211
	v_or_b32_e32 v172, 0x5800, v158
	v_mov_b32_e32 v173, v211
	v_or_b32_e32 v174, 0x8000, v158
	v_mov_b32_e32 v175, v211
	s_lshl_b64 s[6:7], s[46:47], 11
	s_waitcnt lgkmcnt(0)
	ds_read_b128 v[32:35], v221
	ds_read_b128 v[36:39], v221 offset:32
	s_add_u32 s5, s76, s6
	s_addc_u32 s6, s77, s7
	s_lshl_b32 s4, s4, 1
	s_add_u32 s4, s5, s4
	s_addc_u32 s5, s6, 0
	v_mov_b32_e32 v193, v211
	v_lshl_add_u64 v[40:41], s[4:5], 0, v[192:193]
	s_waitcnt lgkmcnt(1)
	v_mul_f32_e32 v0, v0, v32
	v_mul_f32_e32 v16, v16, v32
	v_lshl_add_u64 v[42:43], v[40:41], 0, v[158:159]
	v_cvt_pk_bf16_f32 v0, v0, s0
	v_cvt_pk_bf16_f32 v16, v16, s0
	global_store_short v[42:43], v0, off offset:64
	v_mul_f32_e32 v0, v17, v33
	global_store_short v[42:43], v16, off
	v_cvt_pk_bf16_f32 v0, v0, s0
	v_lshl_add_u64 v[16:17], v[40:41], 0, v[160:161]
	global_store_short v[16:17], v0, off
	v_mul_f32_e32 v0, v1, v33
	v_cvt_pk_bf16_f32 v0, v0, s0
	global_store_short v[16:17], v0, off offset:64
	v_mul_f32_e32 v0, v18, v34
	v_mul_f32_e32 v2, v2, v34
	v_cvt_pk_bf16_f32 v16, v0, s0
	v_lshl_add_u64 v[0:1], v[40:41], 0, v[162:163]
	v_cvt_pk_bf16_f32 v2, v2, s0
	global_store_short v[0:1], v16, off
	global_store_short v[0:1], v2, off offset:64
	v_mul_f32_e32 v0, v19, v35
	v_cvt_pk_bf16_f32 v2, v0, s0
	v_lshl_add_u64 v[0:1], v[40:41], 0, v[164:165]
	global_store_short v[0:1], v2, off
	v_mul_f32_e32 v2, v3, v35
	v_cvt_pk_bf16_f32 v2, v2, s0
	global_store_short v[0:1], v2, off offset:64
	s_waitcnt lgkmcnt(0)
	v_mul_f32_e32 v0, v20, v36
	v_cvt_pk_bf16_f32 v2, v0, s0
	v_lshl_add_u64 v[0:1], v[40:41], 0, v[166:167]
	global_store_short v[0:1], v2, off
	v_mul_f32_e32 v2, v4, v36
	v_cvt_pk_bf16_f32 v2, v2, s0
	global_store_short v[0:1], v2, off offset:64
	v_mul_f32_e32 v0, v21, v37
	v_cvt_pk_bf16_f32 v2, v0, s0
	v_lshl_add_u64 v[0:1], v[40:41], 0, v[168:169]
	global_store_short v[0:1], v2, off
	v_mul_f32_e32 v2, v5, v37
	v_cvt_pk_bf16_f32 v2, v2, s0
	global_store_short v[0:1], v2, off offset:64
	v_mul_f32_e32 v0, v22, v38
	v_cvt_pk_bf16_f32 v2, v0, s0
	v_lshl_add_u64 v[0:1], v[40:41], 0, v[170:171]
	global_store_short v[0:1], v2, off
	v_mul_f32_e32 v2, v6, v38
	v_cvt_pk_bf16_f32 v2, v2, s0
	global_store_short v[0:1], v2, off offset:64
	v_mul_f32_e32 v0, v23, v39
	v_cvt_pk_bf16_f32 v0, v0, s0
	v_lshl_add_u64 v[4:5], v[40:41], 0, v[172:173]
	global_store_short v[4:5], v0, off
	ds_read_b128 v[0:3], v221 offset:64
	v_mul_f32_e32 v6, v7, v39
	v_cvt_pk_bf16_f32 v6, v6, s0
	global_store_short v[4:5], v6, off offset:64
	ds_read_b128 v[4:7], v221 offset:96
	s_waitcnt lgkmcnt(1)
	v_mul_f32_e32 v16, v24, v0
	v_mul_f32_e32 v0, v8, v0
	v_cvt_pk_bf16_f32 v18, v16, s0
	v_lshl_add_u64 v[16:17], v[40:41], 0, v[174:175]
	v_cvt_pk_bf16_f32 v0, v0, s0
	global_store_short v[16:17], v0, off offset:64
	v_mul_f32_e32 v0, v25, v1
	global_store_short v[16:17], v18, off
	v_cvt_pk_bf16_f32 v0, v0, s0
	v_lshl_add_u64 v[16:17], v[40:41], 0, v[176:177]
	global_store_short v[16:17], v0, off
	v_mul_f32_e32 v0, v9, v1
	v_cvt_pk_bf16_f32 v0, v0, s0
	global_store_short v[16:17], v0, off offset:64
	v_mul_f32_e32 v0, v26, v2
	v_mul_f32_e32 v2, v10, v2
	v_cvt_pk_bf16_f32 v8, v0, s0
	v_lshl_add_u64 v[0:1], v[40:41], 0, v[178:179]
	v_cvt_pk_bf16_f32 v2, v2, s0
	global_store_short v[0:1], v8, off
	global_store_short v[0:1], v2, off offset:64
	v_mul_f32_e32 v0, v27, v3
	v_cvt_pk_bf16_f32 v2, v0, s0
	v_lshl_add_u64 v[0:1], v[40:41], 0, v[180:181]
	global_store_short v[0:1], v2, off
	v_mul_f32_e32 v2, v11, v3
	v_cvt_pk_bf16_f32 v2, v2, s0
	global_store_short v[0:1], v2, off offset:64
	s_waitcnt lgkmcnt(0)
	v_mul_f32_e32 v0, v28, v4
	v_cvt_pk_bf16_f32 v2, v0, s0
	v_lshl_add_u64 v[0:1], v[40:41], 0, v[182:183]
	global_store_short v[0:1], v2, off
	v_mul_f32_e32 v2, v12, v4
	v_cvt_pk_bf16_f32 v2, v2, s0
	global_store_short v[0:1], v2, off offset:64
	v_mul_f32_e32 v0, v29, v5
	v_cvt_pk_bf16_f32 v2, v0, s0
	v_lshl_add_u64 v[0:1], v[40:41], 0, v[184:185]
	global_store_short v[0:1], v2, off
	v_mul_f32_e32 v2, v13, v5
	v_cvt_pk_bf16_f32 v2, v2, s0
	global_store_short v[0:1], v2, off offset:64
	v_mul_f32_e32 v0, v30, v6
	v_cvt_pk_bf16_f32 v2, v0, s0
	v_lshl_add_u64 v[0:1], v[40:41], 0, v[186:187]
	global_store_short v[0:1], v2, off
	v_mul_f32_e32 v2, v14, v6
	v_cvt_pk_bf16_f32 v2, v2, s0
	global_store_short v[0:1], v2, off offset:64
	v_mul_f32_e32 v0, v31, v7
	v_cvt_pk_bf16_f32 v2, v0, s0
	v_lshl_add_u64 v[0:1], v[40:41], 0, v[188:189]
	global_store_short v[0:1], v2, off
	v_mul_f32_e32 v2, v15, v7
	v_cvt_pk_bf16_f32 v2, v2, s0
	global_store_short v[0:1], v2, off offset:64
	s_add_i32 s3, s3, s15
	s_cmpk_gt_i32 s3, 0x3ff
	s_cbranch_scc1 .LBB0_314

.LBB0_290:
	s_add_i32 s27, s12, 0
	s_mov_b32 s25, s11
	s_mov_b32 s11, s56
	v_add_u32_e32 v213, s25, v203
	v_add_u32_e32 v214, v213, v204
	ds_read_b128 v[160:163], v214
	ds_read_b128 v[164:167], v214 offset:512
	v_add_u32_e32 v214, v213, v205
	ds_read_b128 v[168:171], v214 offset:2048
	ds_read_b128 v[172:175], v214 offset:2560
	v_add_u32_e32 v212, s27, v97
	s_waitcnt vmcnt(5)
	ds_write_b128 v212, v[122:125]
	s_and_saveexec_b64 s[6:7], s[42:43]
	s_cbranch_execz .LBB0_292
	v_add_u32_e32 v122, s27, v147
	s_waitcnt vmcnt(4)
	ds_write_b128 v122, v[126:129]

.LBB0_299:
	v_add_u32_e32 v193, s25, v203
	s_waitcnt lgkmcnt(5)
	v_mfma_f32_32x32x16_bf16 v[64:79], v[160:163], v[98:101], 0
	v_sub_f32_e32 v32, v32, v222
	v_sub_f32_e32 v33, v33, v222
	v_exp_f32_e32 v32, v32
	v_exp_f32_e32 v33, v33
	s_waitcnt lgkmcnt(4)
	v_mfma_f32_32x32x16_bf16 v[80:95], v[164:167], v[98:101], 0
	v_sub_f32_e32 v34, v34, v222
	v_sub_f32_e32 v35, v35, v222
	v_exp_f32_e32 v34, v34
	v_exp_f32_e32 v35, v35
	s_waitcnt lgkmcnt(3)
	v_mfma_f32_32x32x16_bf16 v[64:79], v[168:171], v[102:105], v[64:79]
	v_add_u32_e32 v212, v193, v206
	ds_read_b128 v[242:245], v212 offset:4096
	ds_read_b128 v[246:249], v212 offset:4608
	v_sub_f32_e32 v36, v36, v222
	v_sub_f32_e32 v37, v37, v222
	v_exp_f32_e32 v36, v36
	v_exp_f32_e32 v37, v37
	s_waitcnt lgkmcnt(4)
	v_mfma_f32_32x32x16_bf16 v[80:95], v[172:175], v[102:105], v[80:95]
	v_sub_f32_e32 v38, v38, v222
	v_sub_f32_e32 v39, v39, v222
	v_exp_f32_e32 v38, v38
	v_exp_f32_e32 v39, v39
	s_waitcnt lgkmcnt(1)
	v_mfma_f32_32x32x16_bf16 v[64:79], v[242:245], v[106:109], v[64:79]
	v_add_u32_e32 v212, v193, v207
	ds_read_b128 v[224:227], v212 offset:6144
	ds_read_b128 v[228:231], v212 offset:6656
	v_sub_f32_e32 v40, v40, v222
	v_sub_f32_e32 v41, v41, v222
	v_exp_f32_e32 v40, v40
	v_exp_f32_e32 v41, v41
	s_waitcnt lgkmcnt(2)
	v_mfma_f32_32x32x16_bf16 v[80:95], v[246:249], v[106:109], v[80:95]
	v_sub_f32_e32 v42, v42, v222
	v_sub_f32_e32 v43, v43, v222
	v_exp_f32_e32 v42, v42
	v_exp_f32_e32 v43, v43
	s_waitcnt lgkmcnt(1)
	v_mfma_f32_32x32x16_bf16 v[64:79], v[224:227], v[110:113], v[64:79]
	v_add_u32_e32 v212, v193, v208
	ds_read_b128 v[242:245], v212 offset:8192
	ds_read_b128 v[246:249], v212 offset:8704
	v_sub_f32_e32 v44, v44, v222
	v_sub_f32_e32 v45, v45, v222
	v_exp_f32_e32 v44, v44
	v_exp_f32_e32 v45, v45
	s_waitcnt lgkmcnt(2)
	v_mfma_f32_32x32x16_bf16 v[80:95], v[228:231], v[110:113], v[80:95]
	v_sub_f32_e32 v46, v46, v222
	v_sub_f32_e32 v47, v47, v222
	v_exp_f32_e32 v46, v46
	v_exp_f32_e32 v47, v47
	s_waitcnt lgkmcnt(1)
	v_mfma_f32_32x32x16_bf16 v[64:79], v[242:245], v[114:117], v[64:79]
	v_add_u32_e32 v193, v193, v209
	ds_read_b128 v[224:227], v193 offset:10240
	ds_read_b128 v[228:231], v193 offset:10752
	v_cvt_pk_bf16_f32 v242, v32, v33
	v_cvt_pk_bf16_f32 v243, v34, v35
	s_waitcnt lgkmcnt(2)
	v_mfma_f32_32x32x16_bf16 v[80:95], v[246:249], v[114:117], v[80:95]
	v_add_f32_e32 v216, v32, v33
	v_add_f32_e32 v217, v34, v35
	v_add_f32_e32 v216, v216, v36
	v_add_f32_e32 v217, v217, v37
	v_add_f32_e32 v216, v216, v38
	v_add_f32_e32 v217, v217, v39
	v_cvt_pk_bf16_f32 v244, v36, v37
	v_cvt_pk_bf16_f32 v245, v38, v39
	s_waitcnt lgkmcnt(1)
	v_mfma_f32_32x32x16_bf16 v[64:79], v[224:227], v[118:121], v[64:79]
	v_add_u32_e32 v193, s11, v218
	ds_read_b64_tr_b16 v[246:247], v193 offset:12288
	ds_read_b64_tr_b16 v[248:249], v193 offset:13824
	v_add_f32_e32 v216, v216, v40
	v_add_f32_e32 v217, v217, v41
	v_add_f32_e32 v216, v216, v42
	v_add_f32_e32 v217, v217, v43
	v_cvt_pk_bf16_f32 v224, v40, v41
	v_cvt_pk_bf16_f32 v225, v42, v43
	s_waitcnt lgkmcnt(2)
	v_mfma_f32_32x32x16_bf16 v[80:95], v[228:231], v[118:121], v[80:95]
	ds_read_b64_tr_b16 v[250:251], v193 offset:12352
	ds_read_b64_tr_b16 v[252:253], v193 offset:13888
	v_add_f32_e32 v216, v216, v44
	v_add_f32_e32 v217, v217, v45
	v_add_f32_e32 v216, v216, v46
	v_add_f32_e32 v217, v217, v47
	v_cvt_pk_bf16_f32 v226, v44, v45
	v_cvt_pk_bf16_f32 v227, v46, v47
	s_waitcnt lgkmcnt(2)
	v_mfma_f32_32x32x16_bf16 v[16:31], v[242:245], v[246:249], v[16:31]
	ds_read_b64_tr_b16 v[228:229], v193 offset:15360
	ds_read_b64_tr_b16 v[230:231], v193 offset:16896
	v_sub_f32_e32 v48, v48, v222
	v_sub_f32_e32 v49, v49, v222
	v_sub_f32_e32 v50, v50, v222
	v_sub_f32_e32 v51, v51, v222
	v_exp_f32_e32 v48, v48
	v_exp_f32_e32 v49, v49
	v_exp_f32_e32 v50, v50
	v_exp_f32_e32 v51, v51
	s_waitcnt lgkmcnt(2)
	v_mfma_f32_32x32x16_bf16 v[0:15], v[242:245], v[250:253], v[0:15]
	ds_read_b64_tr_b16 v[242:243], v193 offset:15424
	ds_read_b64_tr_b16 v[244:245], v193 offset:16960
	v_sub_f32_e32 v52, v52, v222
	v_sub_f32_e32 v53, v53, v222
	v_sub_f32_e32 v54, v54, v222
	v_sub_f32_e32 v55, v55, v222
	v_exp_f32_e32 v52, v52
	v_exp_f32_e32 v53, v53
	v_exp_f32_e32 v54, v54
	v_exp_f32_e32 v55, v55
	s_waitcnt lgkmcnt(2)
	v_mfma_f32_32x32x16_bf16 v[16:31], v[224:227], v[228:231], v[16:31]
	ds_read_b64_tr_b16 v[228:229], v193 offset:18432
	ds_read_b64_tr_b16 v[230:231], v193 offset:19968
	v_sub_f32_e32 v56, v56, v222
	v_sub_f32_e32 v57, v57, v222
	v_sub_f32_e32 v58, v58, v222
	v_sub_f32_e32 v59, v59, v222
	v_exp_f32_e32 v56, v56
	v_exp_f32_e32 v57, v57
	v_exp_f32_e32 v58, v58
	v_exp_f32_e32 v59, v59
	v_cvt_pk_bf16_f32 v246, v48, v49
	v_cvt_pk_bf16_f32 v247, v50, v51
	s_waitcnt lgkmcnt(2)
	v_mfma_f32_32x32x16_bf16 v[0:15], v[224:227], v[242:245], v[0:15]
	ds_read_b64_tr_b16 v[224:225], v193 offset:18496
	ds_read_b64_tr_b16 v[226:227], v193 offset:20032
	v_sub_f32_e32 v60, v60, v222
	v_sub_f32_e32 v61, v61, v222
	v_sub_f32_e32 v62, v62, v222
	v_sub_f32_e32 v63, v63, v222
	v_exp_f32_e32 v60, v60
	v_exp_f32_e32 v61, v61
	v_exp_f32_e32 v62, v62
	v_exp_f32_e32 v63, v63
	v_cvt_pk_bf16_f32 v248, v52, v53
	v_cvt_pk_bf16_f32 v249, v54, v55
	s_waitcnt lgkmcnt(2)
	s_nop 0
	v_mfma_f32_32x32x16_bf16 v[16:31], v[246:249], v[228:231], v[16:31]
	ds_read_b64_tr_b16 v[228:229], v193 offset:21504
	ds_read_b64_tr_b16 v[230:231], v193 offset:23040
	v_add_f32_e32 v216, v216, v48
	v_add_f32_e32 v217, v217, v49
	v_add_f32_e32 v216, v216, v50
	v_add_f32_e32 v217, v217, v51
	v_cvt_pk_bf16_f32 v242, v56, v57
	v_cvt_pk_bf16_f32 v243, v58, v59
	s_waitcnt lgkmcnt(2)
	v_mfma_f32_32x32x16_bf16 v[0:15], v[246:249], v[224:227], v[0:15]
	ds_read_b64_tr_b16 v[224:225], v193 offset:21568
	ds_read_b64_tr_b16 v[226:227], v193 offset:23104
	v_add_f32_e32 v216, v216, v52
	v_add_f32_e32 v217, v217, v53
	v_add_f32_e32 v216, v216, v54
	v_add_f32_e32 v217, v217, v55
	v_cvt_pk_bf16_f32 v244, v60, v61
	v_cvt_pk_bf16_f32 v245, v62, v63
	s_waitcnt lgkmcnt(2)
	s_nop 0
	v_mfma_f32_32x32x16_bf16 v[16:31], v[242:245], v[228:231], v[16:31]
	v_add_f32_e32 v216, v216, v56
	v_add_f32_e32 v217, v217, v57
	v_add_f32_e32 v216, v216, v58
	v_add_f32_e32 v217, v217, v59
	s_waitcnt lgkmcnt(0)
	v_mfma_f32_32x32x16_bf16 v[0:15], v[242:245], v[224:227], v[0:15]
	v_add_f32_e32 v216, v216, v60
	v_add_f32_e32 v217, v217, v61
	v_add_f32_e32 v216, v216, v62
	v_add_f32_e32 v217, v217, v63
	v_add_f32_e32 v216, v216, v217
	v_add_f32_e32 v191, v191, v216
.LBB0_300:
	s_waitcnt lgkmcnt(0)
	s_barrier
	v_add3_u32 v213, s27, v201, v202
	v_add_u32_e32 v214, v213, v204
	ds_read_b128 v[160:163], v214
	ds_read_b128 v[164:167], v214 offset:512
	v_add_u32_e32 v214, v213, v205
	ds_read_b128 v[168:171], v214 offset:2048
	ds_read_b128 v[172:175], v214 offset:2560
	s_add_i32 s16, s11, 0
	v_add_u32_e32 v193, s16, v97
	s_waitcnt vmcnt(5)
	ds_write_b128 v193, v[134:137]
	s_and_saveexec_b64 s[6:7], s[42:43]
	s_cbranch_execz .LBB0_302
	v_add_u32_e32 v134, s16, v147
	s_waitcnt vmcnt(4)
	ds_write_b128 v134, v[138:141]

.LBB0_309:
	v_add3_u32 v212, s27, v201, v202
	v_sub_f32_e32 v36, v64, v193
	v_exp_f32_e32 v64, v36
	v_sub_f32_e32 v36, v65, v193
	v_exp_f32_e32 v65, v36
	s_waitcnt lgkmcnt(5)
	v_mfma_f32_32x32x16_bf16 v[32:47], v[160:163], v[98:101], 0
	v_sub_f32_e32 v52, v66, v193
	v_exp_f32_e32 v66, v52
	v_sub_f32_e32 v52, v67, v193
	v_exp_f32_e32 v67, v52
	s_waitcnt lgkmcnt(4)
	v_mfma_f32_32x32x16_bf16 v[48:63], v[164:167], v[98:101], 0
	s_waitcnt lgkmcnt(3)
	v_mfma_f32_32x32x16_bf16 v[32:47], v[168:171], v[102:105], v[32:47]
	v_add_u32_e32 v213, v212, v206
	ds_read_b128 v[230:233], v213 offset:4096
	ds_read_b128 v[242:245], v213 offset:4608
	v_sub_f32_e32 v68, v68, v193
	v_sub_f32_e32 v69, v69, v193
	v_exp_f32_e32 v68, v68
	v_exp_f32_e32 v69, v69
	s_waitcnt lgkmcnt(4)
	v_mfma_f32_32x32x16_bf16 v[48:63], v[172:175], v[102:105], v[48:63]
	v_sub_f32_e32 v70, v70, v193
	v_sub_f32_e32 v71, v71, v193
	v_exp_f32_e32 v70, v70
	v_exp_f32_e32 v71, v71
	s_waitcnt lgkmcnt(1)
	v_mfma_f32_32x32x16_bf16 v[32:47], v[230:233], v[106:109], v[32:47]
	v_add_u32_e32 v213, v212, v207
	ds_read_b128 v[222:225], v213 offset:6144
	ds_read_b128 v[226:229], v213 offset:6656
	v_sub_f32_e32 v72, v72, v193
	v_sub_f32_e32 v73, v73, v193
	v_exp_f32_e32 v72, v72
	v_exp_f32_e32 v73, v73
	s_waitcnt lgkmcnt(2)
	v_mfma_f32_32x32x16_bf16 v[48:63], v[242:245], v[106:109], v[48:63]
	v_sub_f32_e32 v74, v74, v193
	v_sub_f32_e32 v75, v75, v193
	v_exp_f32_e32 v74, v74
	v_exp_f32_e32 v75, v75
	s_waitcnt lgkmcnt(1)
	v_mfma_f32_32x32x16_bf16 v[32:47], v[222:225], v[110:113], v[32:47]
	v_add_u32_e32 v213, v212, v208
	ds_read_b128 v[230:233], v213 offset:8192
	ds_read_b128 v[242:245], v213 offset:8704
	v_sub_f32_e32 v76, v76, v193
	v_sub_f32_e32 v77, v77, v193
	v_exp_f32_e32 v76, v76
	v_exp_f32_e32 v77, v77
	s_waitcnt lgkmcnt(2)
	v_mfma_f32_32x32x16_bf16 v[48:63], v[226:229], v[110:113], v[48:63]
	v_sub_f32_e32 v78, v78, v193
	v_sub_f32_e32 v79, v79, v193
	v_exp_f32_e32 v78, v78
	v_exp_f32_e32 v79, v79
	s_waitcnt lgkmcnt(1)
	v_mfma_f32_32x32x16_bf16 v[32:47], v[230:233], v[114:117], v[32:47]
	v_add_u32_e32 v212, v212, v209
	ds_read_b128 v[222:225], v212 offset:10240
	ds_read_b128 v[226:229], v212 offset:10752
	v_cvt_pk_bf16_f32 v230, v64, v65
	v_cvt_pk_bf16_f32 v231, v66, v67
	s_waitcnt lgkmcnt(2)
	v_mfma_f32_32x32x16_bf16 v[48:63], v[242:245], v[114:117], v[48:63]
	v_add_f32_e32 v216, v64, v65
	v_add_f32_e32 v217, v66, v67
	v_add_f32_e32 v216, v216, v68
	v_add_f32_e32 v217, v217, v69
	v_add_f32_e32 v216, v216, v70
	v_add_f32_e32 v217, v217, v71
	v_cvt_pk_bf16_f32 v232, v68, v69
	v_cvt_pk_bf16_f32 v233, v70, v71
	s_waitcnt lgkmcnt(1)
	v_mfma_f32_32x32x16_bf16 v[32:47], v[222:225], v[118:121], v[32:47]
	v_add_u32_e32 v252, s25, v218
	ds_read_b64_tr_b16 v[242:243], v252 offset:12288
	ds_read_b64_tr_b16 v[244:245], v252 offset:13824
	v_add_f32_e32 v216, v216, v72
	v_add_f32_e32 v217, v217, v73
	v_add_f32_e32 v216, v216, v74
	v_add_f32_e32 v217, v217, v75
	v_cvt_pk_bf16_f32 v222, v72, v73
	v_cvt_pk_bf16_f32 v223, v74, v75
	s_waitcnt lgkmcnt(2)
	v_mfma_f32_32x32x16_bf16 v[48:63], v[226:229], v[118:121], v[48:63]
	ds_read_b64_tr_b16 v[246:247], v252 offset:12352
	ds_read_b64_tr_b16 v[248:249], v252 offset:13888
	v_add_f32_e32 v216, v216, v76
	v_add_f32_e32 v217, v217, v77
	v_add_f32_e32 v216, v216, v78
	v_add_f32_e32 v217, v217, v79
	v_cvt_pk_bf16_f32 v224, v76, v77
	v_cvt_pk_bf16_f32 v225, v78, v79
	s_waitcnt lgkmcnt(2)
	v_mfma_f32_32x32x16_bf16 v[16:31], v[230:233], v[242:245], v[16:31]
	ds_read_b64_tr_b16 v[226:227], v252 offset:15360
	ds_read_b64_tr_b16 v[228:229], v252 offset:16896
	v_sub_f32_e32 v80, v80, v193
	v_sub_f32_e32 v81, v81, v193
	v_sub_f32_e32 v82, v82, v193
	v_sub_f32_e32 v83, v83, v193
	v_exp_f32_e32 v80, v80
	v_exp_f32_e32 v81, v81
	v_exp_f32_e32 v82, v82
	v_exp_f32_e32 v83, v83
	s_waitcnt lgkmcnt(2)
	v_mfma_f32_32x32x16_bf16 v[0:15], v[230:233], v[246:249], v[0:15]
	ds_read_b64_tr_b16 v[230:231], v252 offset:15424
	ds_read_b64_tr_b16 v[232:233], v252 offset:16960
	v_sub_f32_e32 v84, v84, v193
	v_sub_f32_e32 v85, v85, v193
	v_sub_f32_e32 v86, v86, v193
	v_sub_f32_e32 v87, v87, v193
	v_exp_f32_e32 v84, v84
	v_exp_f32_e32 v85, v85
	v_exp_f32_e32 v86, v86
	v_exp_f32_e32 v87, v87
	s_waitcnt lgkmcnt(2)
	v_mfma_f32_32x32x16_bf16 v[16:31], v[222:225], v[226:229], v[16:31]
	ds_read_b64_tr_b16 v[226:227], v252 offset:18432
	ds_read_b64_tr_b16 v[228:229], v252 offset:19968
	v_sub_f32_e32 v88, v88, v193
	v_sub_f32_e32 v89, v89, v193
	v_sub_f32_e32 v90, v90, v193
	v_sub_f32_e32 v91, v91, v193
	v_exp_f32_e32 v88, v88
	v_exp_f32_e32 v89, v89
	v_exp_f32_e32 v90, v90
	v_exp_f32_e32 v91, v91
	v_cvt_pk_bf16_f32 v242, v80, v81
	v_cvt_pk_bf16_f32 v243, v82, v83
	s_waitcnt lgkmcnt(2)
	v_mfma_f32_32x32x16_bf16 v[0:15], v[222:225], v[230:233], v[0:15]
	ds_read_b64_tr_b16 v[222:223], v252 offset:18496
	ds_read_b64_tr_b16 v[224:225], v252 offset:20032
	v_sub_f32_e32 v92, v92, v193
	v_sub_f32_e32 v93, v93, v193
	v_sub_f32_e32 v94, v94, v193
	v_sub_f32_e32 v95, v95, v193
	v_exp_f32_e32 v92, v92
	v_exp_f32_e32 v93, v93
	v_exp_f32_e32 v94, v94
	v_exp_f32_e32 v95, v95
	v_cvt_pk_bf16_f32 v244, v84, v85
	v_cvt_pk_bf16_f32 v245, v86, v87
	s_waitcnt lgkmcnt(2)
	s_nop 0
	v_mfma_f32_32x32x16_bf16 v[16:31], v[242:245], v[226:229], v[16:31]
	ds_read_b64_tr_b16 v[226:227], v252 offset:21504
	ds_read_b64_tr_b16 v[228:229], v252 offset:23040
	v_add_f32_e32 v216, v216, v80
	v_add_f32_e32 v217, v217, v81
	v_add_f32_e32 v216, v216, v82
	v_add_f32_e32 v217, v217, v83
	v_cvt_pk_bf16_f32 v230, v88, v89
	v_cvt_pk_bf16_f32 v231, v90, v91
	s_waitcnt lgkmcnt(2)
	v_mfma_f32_32x32x16_bf16 v[0:15], v[242:245], v[222:225], v[0:15]
	ds_read_b64_tr_b16 v[222:223], v252 offset:21568
	ds_read_b64_tr_b16 v[224:225], v252 offset:23104
	v_add_f32_e32 v216, v216, v84
	v_add_f32_e32 v217, v217, v85
	v_add_f32_e32 v216, v216, v86
	v_add_f32_e32 v217, v217, v87
	v_cvt_pk_bf16_f32 v232, v92, v93
	v_cvt_pk_bf16_f32 v233, v94, v95
	s_waitcnt lgkmcnt(2)
	s_nop 0
	v_mfma_f32_32x32x16_bf16 v[16:31], v[230:233], v[226:229], v[16:31]
	v_add_f32_e32 v216, v216, v88
	v_add_f32_e32 v217, v217, v89
	v_add_f32_e32 v216, v216, v90
	v_add_f32_e32 v217, v217, v91
	s_waitcnt lgkmcnt(0)
	v_mfma_f32_32x32x16_bf16 v[0:15], v[230:233], v[222:225], v[0:15]
	v_add_f32_e32 v216, v216, v92
	v_add_f32_e32 v217, v217, v93
	v_add_f32_e32 v216, v216, v94
	v_add_f32_e32 v217, v217, v95
	v_add_f32_e32 v216, v216, v217
	v_add_f32_e32 v191, v191, v216
